# v13 + attention tail-wait deferral: ENDW(NT-2) lets V(NT-1) fly (vmcnt(VH)), vmcnt(0)+barrier moved in front of the drain's first V read
# speedup vs baseline: 1.0005x; 1.0005x over previous
;   #define RSCALE(t) do{ if(HAS_BIAS&&((t)==tn0||(t)==tn1)){ const float f_=__builtin_amdgcn_exp2f(CREG((t)-1)-CREG(t)); l_reg*=f_; \
;     _Pragma("unroll") for(int d_=0;d_<2*VH;++d_) _Pragma("unroll") for(int r=0;r<16;++r)o[d_][r]*=f_; } }while(0)
;   #define ROT() do{sv_prev=sv_cur;sv_cur=sv_next;sv_next=(sv_next==2*VSL)?0:sv_next+VSL;}while(0)
;   #define WAITFULL() do{ if(VH==1){WAIT_BAR(2);}else{WAIT_BAR(3);} }while(0)
;   #define ENDW(tt) do{ if((tt)+3<NT){WAITFULL();} else if((tt)+2<NT){ if(VH==1){WAIT_BAR(1);}else{WAIT_BAR(2);} } else {WAIT_BAR(0);} }while(0)
; template<int VH,bool HAS_BIAS,int MODE> __device__ __forceinline__ void attn_unit2(const bf16*Qb,int qp,const bf16*__restrict__ Kb,int kp,const bf16*__restrict__ Vb,int vp,bf16*Ob,int op,int q0,int NT,const float*relb,char*shm,float lam,const float*subg,float gmul){
;     ...
;   int t=1;
;   for(;t+5<NT;t+=2){
;     STEP(pB0,pB1,pA0,pA1,t,true,true,true);     WAITFULL(); RSCALE(t);   ROT();
;     STEP(pA0,pA1,pB0,pB1,t+1,true,true,true);   WAITFULL(); RSCALE(t+1); ROT();
;   }
;   for(;t+1<NT;t+=2){
;     STEP(pB0,pB1,pA0,pA1,t,(t+3<NT),(t+1<NT),(t+1<NT));       ENDW(t);   RSCALE(t);   ROT();
;     STEP(pA0,pA1,pB0,pB1,t+1,(t+4<NT),(t+2<NT),(t+2<NT));     ENDW(t+1); RSCALE(t+1); ROT();
.LBB0_634:
	s_waitcnt lgkmcnt(6)
	v_mfma_f32_32x32x16_bf16 v[0:15], v[100:103], v[88:91], v[0:15]
	v_exp_f32_e32 v32, v32
	v_exp_f32_e32 v33, v33
	v_exp_f32_e32 v34, v34
	v_exp_f32_e32 v35, v35
	s_waitcnt lgkmcnt(4)
	v_mfma_f32_32x32x16_bf16 v[16:31], v[100:103], v[84:87], v[16:31]
	v_exp_f32_e32 v36, v36
	v_exp_f32_e32 v37, v37
	v_exp_f32_e32 v38, v38
	v_exp_f32_e32 v39, v39
	s_waitcnt lgkmcnt(2)
	v_mfma_f32_32x32x16_bf16 v[0:15], v[96:99], v[68:71], v[0:15]
	v_exp_f32_e32 v40, v40
	v_exp_f32_e32 v41, v41
	v_exp_f32_e32 v42, v42
	v_exp_f32_e32 v43, v43
	s_waitcnt lgkmcnt(0)
	v_mfma_f32_32x32x16_bf16 v[16:31], v[96:99], v[64:67], v[16:31]
	v_exp_f32_e32 v44, v44
	v_exp_f32_e32 v45, v45
	v_exp_f32_e32 v46, v46
	v_exp_f32_e32 v47, v47
	s_mov_b64 s[44:45], -1
	s_and_b64 vcc, exec, s[42:43]
	s_cbranch_vccz .LBB0_640
	s_mov_b64 s[42:43], -1
	s_and_b64 vcc, exec, s[40:41]
	s_cbranch_vccz .LBB0_637
	s_waitcnt vmcnt(1) lgkmcnt(0)
	s_barrier
	s_mov_b64 s[42:43], 0

; #define SBAR() __builtin_amdgcn_sched_barrier(0)
;   #define RSCALE(t) do{ if(HAS_BIAS&&((t)==tn0||(t)==tn1)){ const float f_=__builtin_amdgcn_exp2f(CREG((t)-1)-CREG(t)); l_reg*=f_; \
;     _Pragma("unroll") for(int d_=0;d_<2*VH;++d_) _Pragma("unroll") for(int r=0;r<16;++r)o[d_][r]*=f_; } }while(0)
;   #define PKW(P,B) cvtpk_s(P[B],P[B+1])
; template<int VH,bool HAS_BIAS,int MODE> __device__ __forceinline__ void attn_unit2(const bf16*Qb,int qp,const bf16*__restrict__ Kb,int kp,const bf16*__restrict__ Vb,int vp,bf16*Ob,int op,int q0,int NT,const float*relb,char*shm,float lam,const float*subg,float gmul){
;     ...
;   STEP(pB0,pB1,pA0,pA1,NT-1,false,false,false); RSCALE(NT-1);
;   { float sacc=pB0[0]+pB0[1]; _Pragma("unroll") for(int r=2;r<16;++r)sacc+=pB0[r]; _Pragma("unroll") for(int r=0;r<16;++r)sacc+=pB1[r]; l_reg+=sacc;
;     pw0=(u32x4){PKW(pB0,0),PKW(pB0,2),PKW(pB0,4),PKW(pB0,6)};pw1=(u32x4){PKW(pB0,8),PKW(pB0,10),PKW(pB0,12),PKW(pB0,14)};pw2=(u32x4){PKW(pB1,0),PKW(pB1,2),PKW(pB1,4),PKW(pB1,6)};pw3=(u32x4){PKW(pB1,8),PKW(pB1,10),PKW(pB1,12),PKW(pB1,14)};
;     SBAR(); pv(o,vb0+sv_cur,PAF(0),PAF(1),PAF(2),PAF(3)); if(VH==2){ SBAR(); pv(o+2*(VH-1),vb0+sv_cur+8192,PAF(0),PAF(1),PAF(2),PAF(3)); } }
.LBB0_645:
	s_and_b32 s12, s52, 0x3fffffc0
	s_cmp_lg_u32 0, -1
	s_cselect_b32 s13, 0, 0
	s_lshl_b32 s12, s12, 2
	s_add_i32 s13, s13, 0x8000
	s_add_i32 s20, s12, 0
	v_add3_u32 v148, v166, s13, v165
	v_add_u32_e32 v149, s60, v167
	ds_read_b64_tr_b16 v[140:141], v149 offset:32768
	ds_read_b64_tr_b16 v[142:143], v149 offset:33280
	v_add_f32_e32 v64, v48, v49
	v_add_f32_e32 v64, v50, v64
	v_add_f32_e32 v64, v51, v64
	v_add_f32_e32 v64, v52, v64
	v_add_f32_e32 v84, v53, v64
	v_cvt_pk_bf16_f32 v108, v48, v49
	v_cvt_pk_bf16_f32 v109, v50, v51
	s_waitcnt lgkmcnt(5)
	v_mfma_f32_32x32x16_bf16 v[64:79], v[80:83], v[124:127], 0
	ds_read_b64_tr_b16 v[48:49], v149 offset:36864
	ds_read_b64_tr_b16 v[50:51], v149 offset:37376
	v_add_f32_e32 v80, v54, v84
	v_add_f32_e32 v80, v55, v80
	v_add_f32_e32 v80, v56, v80
	v_add_f32_e32 v96, v57, v80
	v_cvt_pk_bf16_f32 v110, v52, v53
	v_cvt_pk_bf16_f32 v111, v54, v55
	s_waitcnt lgkmcnt(6)
	v_mfma_f32_32x32x16_bf16 v[80:95], v[136:139], v[124:127], 0
	ds_read_b128 v[136:139], v164 offset:28672
	ds_read_b128 v[144:147], v164 offset:29184
	ds_read_b64_tr_b16 v[124:125], v149 offset:33792
	ds_read_b64_tr_b16 v[126:127], v149 offset:34304
	v_add_f32_e32 v52, v58, v96
	v_add_f32_e32 v52, v59, v52
	v_add_f32_e32 v52, v60, v52
	v_add_f32_e32 v96, v61, v52
	v_cvt_pk_bf16_f32 v104, v56, v57
	v_cvt_pk_bf16_f32 v105, v58, v59
	s_waitcnt lgkmcnt(9)
	v_mfma_f32_32x32x16_bf16 v[64:79], v[132:135], v[120:123], v[64:79]
	ds_read_b64_tr_b16 v[52:53], v149 offset:37888
	ds_read_b64_tr_b16 v[54:55], v149 offset:38400
	v_add_f32_e32 v56, v62, v96
	v_add_f32_e32 v56, v63, v56
	v_add_f32_e32 v56, v32, v56
	v_add_f32_e32 v96, v33, v56
	v_cvt_pk_bf16_f32 v106, v60, v61
	v_cvt_pk_bf16_f32 v107, v62, v63
	s_waitcnt lgkmcnt(10)
	v_mfma_f32_32x32x16_bf16 v[80:95], v[128:131], v[120:123], v[80:95]
	ds_read_b128 v[60:63], v164 offset:30720
	ds_read_b128 v[120:123], v164 offset:31232
	ds_read_b64_tr_b16 v[56:57], v149 offset:34816
	ds_read_b64_tr_b16 v[58:59], v149 offset:35328
	v_add_f32_e32 v96, v34, v96
	v_add_f32_e32 v96, v35, v96
	v_add_f32_e32 v96, v36, v96
	v_add_f32_e32 v96, v37, v96
	v_cvt_pk_bf16_f32 v100, v32, v33
	v_cvt_pk_bf16_f32 v101, v34, v35
	s_waitcnt lgkmcnt(9)
	v_mfma_f32_32x32x16_bf16 v[64:79], v[136:139], v[116:119], v[64:79]
	ds_read_b64_tr_b16 v[32:33], v149 offset:38912
	ds_read_b64_tr_b16 v[34:35], v149 offset:39424
	v_add_f32_e32 v96, v38, v96
	v_add_f32_e32 v96, v39, v96
	v_add_f32_e32 v96, v40, v96
	v_add_f32_e32 v96, v41, v96
	v_cvt_pk_bf16_f32 v102, v36, v37
	v_cvt_pk_bf16_f32 v103, v38, v39
	s_waitcnt lgkmcnt(10)
	v_mfma_f32_32x32x16_bf16 v[80:95], v[144:147], v[116:119], v[80:95]
	ds_read_b64_tr_b16 v[116:117], v149 offset:35840
	ds_read_b64_tr_b16 v[118:119], v149 offset:36352
	v_add_f32_e32 v36, v42, v96
	v_add_f32_e32 v36, v43, v36
	v_add_f32_e32 v36, v44, v36
	v_add_f32_e32 v128, v45, v36
	v_cvt_pk_bf16_f32 v96, v40, v41
	v_cvt_pk_bf16_f32 v97, v42, v43
	s_waitcnt lgkmcnt(7)
	v_mfma_f32_32x32x16_bf16 v[64:79], v[60:63], v[112:115], v[64:79]
	ds_read_b64_tr_b16 v[36:37], v149 offset:39936
	ds_read_b64_tr_b16 v[38:39], v149 offset:40448
	v_add_f32_e32 v40, v46, v128
	v_add_f32_e32 v40, v47, v40
	v_add_f32_e32 v40, 0, v40
	v_cvt_pk_bf16_f32 v98, v44, v45
	v_cvt_pk_bf16_f32 v99, v46, v47
	s_waitcnt lgkmcnt(8)
	v_mfma_f32_32x32x16_bf16 v[80:95], v[120:123], v[112:115], v[80:95]
	s_nop 2
	v_exp_f32_e32 v64, v64
	v_exp_f32_e32 v65, v65
	v_exp_f32_e32 v66, v66
	v_exp_f32_e32 v67, v67
	s_nop 0
	v_exp_f32_e32 v68, v68
	v_exp_f32_e32 v69, v69
	v_exp_f32_e32 v70, v70
	v_exp_f32_e32 v71, v71
	s_nop 0
	v_exp_f32_e32 v72, v72
	v_exp_f32_e32 v73, v73
	v_exp_f32_e32 v74, v74
	v_exp_f32_e32 v75, v75
	s_nop 0
	v_exp_f32_e32 v76, v76
	v_exp_f32_e32 v77, v77
	v_exp_f32_e32 v78, v78
	v_exp_f32_e32 v79, v79
	v_exp_f32_e32 v80, v80
	v_exp_f32_e32 v81, v81
	v_exp_f32_e32 v82, v82
	v_exp_f32_e32 v83, v83
	s_nop 0
	v_exp_f32_e32 v84, v84
	v_exp_f32_e32 v85, v85
	v_exp_f32_e32 v86, v86
	v_exp_f32_e32 v87, v87
	s_nop 0
	v_exp_f32_e32 v88, v88
	v_exp_f32_e32 v89, v89
	v_exp_f32_e32 v90, v90
	v_exp_f32_e32 v91, v91
	s_nop 0
	v_exp_f32_e32 v92, v92
	v_exp_f32_e32 v93, v93
	v_exp_f32_e32 v94, v94
	v_exp_f32_e32 v95, v95
	v_mfma_f32_32x32x16_bf16 v[0:15], v[108:111], v[140:143], v[0:15]
	v_add_f32_e32 v41, v64, v65
	v_add_f32_e32 v41, v66, v41
	v_add_f32_e32 v41, v67, v41
	v_add_f32_e32 v41, v68, v41
	v_add_f32_e32 v41, v69, v41
	v_add_f32_e32 v41, v70, v41
	v_add_f32_e32 v41, v71, v41
	v_mfma_f32_32x32x16_bf16 v[16:31], v[108:111], v[48:51], v[16:31]
	v_add_f32_e32 v41, v72, v41
	v_add_f32_e32 v41, v73, v41
	v_add_f32_e32 v41, v74, v41
	v_add_f32_e32 v41, v75, v41
	v_add_f32_e32 v41, v76, v41
	v_add_f32_e32 v41, v77, v41
	v_add_f32_e32 v41, v78, v41
	v_mfma_f32_32x32x16_bf16 v[0:15], v[104:107], v[124:127], v[0:15]
	v_add_f32_e32 v41, v79, v41
	v_add_f32_e32 v41, v80, v41
	v_add_f32_e32 v41, v81, v41
	v_add_f32_e32 v41, v82, v41
	v_add_f32_e32 v41, v83, v41
	v_add_f32_e32 v41, v84, v41
	v_add_f32_e32 v41, v85, v41
	v_mfma_f32_32x32x16_bf16 v[16:31], v[104:107], v[52:55], v[16:31]
	v_add_f32_e32 v41, v86, v41
	v_add_f32_e32 v41, v87, v41
	v_add_f32_e32 v41, v88, v41
	v_add_f32_e32 v41, v89, v41
	v_add_f32_e32 v41, v90, v41
	v_add_f32_e32 v41, v91, v41
	v_add_f32_e32 v41, v92, v41
	s_waitcnt lgkmcnt(6)
	v_mfma_f32_32x32x16_bf16 v[0:15], v[100:103], v[56:59], v[0:15]
	v_add_f32_e32 v41, v93, v41
	v_add_f32_e32 v41, v94, v41
	v_add_f32_e32 v41, v95, v41
	v_add_f32_e32 v40, v168, v40
	v_add_f32_e32 v40, v40, v41
	v_cvt_pk_bf16_f32 v42, v64, v65
	v_cvt_pk_bf16_f32 v43, v66, v67
	s_waitcnt lgkmcnt(4)
	v_mfma_f32_32x32x16_bf16 v[16:31], v[100:103], v[32:35], v[16:31]
	v_cvt_pk_bf16_f32 v32, v80, v81
	v_cvt_pk_bf16_f32 v44, v68, v69
	v_cvt_pk_bf16_f32 v45, v70, v71
	v_cvt_pk_bf16_f32 v46, v72, v73
	v_cvt_pk_bf16_f32 v47, v74, v75
	v_cvt_pk_bf16_f32 v48, v76, v77
	v_cvt_pk_bf16_f32 v49, v78, v79
	s_waitcnt lgkmcnt(2)
	v_mfma_f32_32x32x16_bf16 v[0:15], v[96:99], v[116:119], v[0:15]
	v_cvt_pk_bf16_f32 v33, v82, v83
	v_cvt_pk_bf16_f32 v34, v84, v85
	v_cvt_pk_bf16_f32 v35, v86, v87
	v_cvt_pk_bf16_f32 v50, v88, v89
	v_cvt_pk_bf16_f32 v51, v90, v91
	v_cvt_pk_bf16_f32 v52, v92, v93
	v_cvt_pk_bf16_f32 v53, v94, v95
	s_waitcnt lgkmcnt(0)
	v_mfma_f32_32x32x16_bf16 v[16:31], v[96:99], v[36:39], v[16:31]
	v_add3_u32 v41, v148, v163, s56
	s_waitcnt vmcnt(0)
	s_barrier
; #define SBAR() __builtin_amdgcn_sched_barrier(0)
; __device__ __forceinline__ void pv(f32x16*o,int vb,bf16x8 pa0,bf16x8 pa1,bf16x8 pa2,bf16x8 pa3){
;   #pragma unroll
;   for(int d0=0;d0<2;++d0){s16x4 lo[4],hi[4];
;     #pragma unroll
;     for(int ks=0;ks<4;++ks){
;       asm volatile("ds_read_b64_tr_b16 %0,%1 offset:%c2":"=&v"(lo[ks]):"v"(vb),"i"(d0*4096+ks*1024):"memory");
;       asm volatile("ds_read_b64_tr_b16 %0,%1 offset:%c2":"=&v"(hi[ks]):"v"(vb),"i"(d0*4096+ks*1024+512):"memory");}
;     asm volatile("s_waitcnt lgkmcnt(0)":::"memory");SBAR();
;     ...
;     o[d0]=__builtin_amdgcn_mfma_f32_32x32x16_bf16(pa0,PK(0),o[d0],0,0,0);
;     o[d0]=__builtin_amdgcn_mfma_f32_32x32x16_bf16(pa1,PK(1),o[d0],0,0,0);
;     o[d0]=__builtin_amdgcn_mfma_f32_32x32x16_bf16(pa2,PK(2),o[d0],0,0,0);
;     o[d0]=__builtin_amdgcn_mfma_f32_32x32x16_bf16(pa3,PK(3),o[d0],0,0,0);
;     ...
;   }
; }
; template<int VH,bool HAS_BIAS,int MODE> __device__ __forceinline__ void attn_unit2(const bf16*Qb,int qp,const bf16*__restrict__ Kb,int kp,const bf16*__restrict__ Vb,int vp,bf16*Ob,int op,int q0,int NT,const float*relb,char*shm,float lam,const float*subg,float gmul){
;     ...
;   {auto rr=__builtin_amdgcn_permlane32_swap(__float_as_uint(l_reg),__float_as_uint(l_reg),false,false);l_reg=__uint_as_float(rr[0])+__uint_as_float(rr[1]);}
;   if(hi==0)wsf[32+r32]=l_reg;
;   asm volatile("s_waitcnt lgkmcnt(0)\n\ts_barrier":::"memory");
	ds_read_b64_tr_b16 v[36:37],v41 offset:0
	ds_read_b64_tr_b16 v[38:39],v41 offset:512
	ds_read_b64_tr_b16 v[54:55],v41 offset:1024
	ds_read_b64_tr_b16 v[56:57],v41 offset:1536
	ds_read_b64_tr_b16 v[58:59],v41 offset:2048
	ds_read_b64_tr_b16 v[60:61],v41 offset:2560
	ds_read_b64_tr_b16 v[62:63],v41 offset:3072
	ds_read_b64_tr_b16 v[64:65],v41 offset:3584
	s_waitcnt lgkmcnt(0)
	s_nop 0
	v_mfma_f32_32x32x16_bf16 v[0:15], v[42:45], v[36:39], v[0:15]
	ds_read_b64_tr_b16 v[36:37],v41 offset:4096
	ds_read_b64_tr_b16 v[38:39],v41 offset:4608
	v_mfma_f32_32x32x16_bf16 v[0:15], v[46:49], v[54:57], v[0:15]
	ds_read_b64_tr_b16 v[54:55],v41 offset:5120
	ds_read_b64_tr_b16 v[56:57],v41 offset:5632
	v_mfma_f32_32x32x16_bf16 v[0:15], v[32:35], v[58:61], v[0:15]
	ds_read_b64_tr_b16 v[58:59],v41 offset:6144
	ds_read_b64_tr_b16 v[60:61],v41 offset:6656
	ds_read_b64_tr_b16 v[66:67],v41 offset:7168
	ds_read_b64_tr_b16 v[68:69],v41 offset:7680
	s_waitcnt lgkmcnt(0)
	v_mfma_f32_32x32x16_bf16 v[0:15], v[50:53], v[62:65], v[0:15]
	v_mfma_f32_32x32x16_bf16 v[16:31], v[42:45], v[36:39], v[16:31]
	v_cmp_gt_u32_e32 vcc, 32, v158
	v_mfma_f32_32x32x16_bf16 v[16:31], v[46:49], v[54:57], v[16:31]
	v_mfma_f32_32x32x16_bf16 v[16:31], v[32:35], v[58:61], v[16:31]
	v_mov_b32_e32 v32, v40
	s_nop 1
	v_permlane32_swap_b32_e32 v40, v32
	v_mfma_f32_32x32x16_bf16 v[16:31], v[50:53], v[66:69], v[16:31]
	s_and_saveexec_b64 s[12:13], vcc
	s_cbranch_execz .LBB0_609
	v_lshl_add_u32 v33, v161, 2, s20
	v_add_f32_e32 v32, v40, v32
	ds_write_b32 v33, v32 offset:57472
	s_branch .LBB0_609

.LBB0_1122:
	s_waitcnt lgkmcnt(14)
	v_mfma_f32_32x32x16_bf16 v[18:33], v[142:145], v[110:113], v[18:33]
	v_exp_f32_e32 v66, v66
	v_exp_f32_e32 v67, v67
	s_waitcnt lgkmcnt(12)
	v_mfma_f32_32x32x16_bf16 v[2:17], v[142:145], v[174:177], v[2:17]
	v_exp_f32_e32 v68, v68
	v_exp_f32_e32 v69, v69
	s_waitcnt lgkmcnt(10)
	v_mfma_f32_32x32x16_bf16 v[18:33], v[138:141], v[118:121], v[18:33]
	v_exp_f32_e32 v70, v70
	v_exp_f32_e32 v71, v71
	s_waitcnt lgkmcnt(8)
	v_mfma_f32_32x32x16_bf16 v[2:17], v[138:141], v[122:125], v[2:17]
	v_exp_f32_e32 v72, v72
	v_exp_f32_e32 v73, v73
	s_waitcnt lgkmcnt(6)
	v_mfma_f32_32x32x16_bf16 v[18:33], v[134:137], v[126:129], v[18:33]
	v_exp_f32_e32 v74, v74
	v_exp_f32_e32 v75, v75
	s_waitcnt lgkmcnt(4)
	v_mfma_f32_32x32x16_bf16 v[2:17], v[134:137], v[98:101], v[2:17]
	v_exp_f32_e32 v76, v76
	v_exp_f32_e32 v77, v77
	s_waitcnt lgkmcnt(2)
	v_mfma_f32_32x32x16_bf16 v[18:33], v[130:133], v[102:105], v[18:33]
	v_exp_f32_e32 v78, v78
	v_exp_f32_e32 v79, v79
	s_waitcnt lgkmcnt(0)
	v_mfma_f32_32x32x16_bf16 v[2:17], v[130:133], v[106:109], v[2:17]
	v_exp_f32_e32 v80, v80
	v_exp_f32_e32 v81, v81
	s_mov_b64 s[54:55], -1
	s_and_b64 vcc, exec, s[42:43]
	s_cbranch_vccz .LBB0_1128
	s_mov_b64 s[42:43], -1
	s_and_b64 vcc, exec, s[10:11]
	s_cbranch_vccz .LBB0_1125
	s_waitcnt vmcnt(2) lgkmcnt(0)
	s_barrier
	s_mov_b64 s[42:43], 0

; #define SBAR() __builtin_amdgcn_sched_barrier(0)
;   #define PKW(P,B) cvtpk_s(P[B],P[B+1])
; __device__ __forceinline__ void pv(f32x16*o,int vb,bf16x8 pa0,bf16x8 pa1,bf16x8 pa2,bf16x8 pa3){
;   #pragma unroll
;   for(int d0=0;d0<2;++d0){s16x4 lo[4],hi[4];
;     #pragma unroll
;     for(int ks=0;ks<4;++ks){
;       asm volatile("ds_read_b64_tr_b16 %0,%1 offset:%c2":"=&v"(lo[ks]):"v"(vb),"i"(d0*4096+ks*1024):"memory");
;       asm volatile("ds_read_b64_tr_b16 %0,%1 offset:%c2":"=&v"(hi[ks]):"v"(vb),"i"(d0*4096+ks*1024+512):"memory");}
;     asm volatile("s_waitcnt lgkmcnt(0)":::"memory");SBAR();
;     ...
;     o[d0]=__builtin_amdgcn_mfma_f32_32x32x16_bf16(pa0,PK(0),o[d0],0,0,0);
;     o[d0]=__builtin_amdgcn_mfma_f32_32x32x16_bf16(pa1,PK(1),o[d0],0,0,0);
;     o[d0]=__builtin_amdgcn_mfma_f32_32x32x16_bf16(pa2,PK(2),o[d0],0,0,0);
;     o[d0]=__builtin_amdgcn_mfma_f32_32x32x16_bf16(pa3,PK(3),o[d0],0,0,0);
;     ...
;   }
; }
; template<int VH,bool HAS_BIAS,int MODE> __device__ __forceinline__ void attn_unit2(const bf16*Qb,int qp,const bf16*__restrict__ Kb,int kp,const bf16*__restrict__ Vb,int vp,bf16*Ob,int op,int q0,int NT,const float*relb,char*shm,float lam,const float*subg,float gmul){
;     ...
;   { float sacc=pB0[0]+pB0[1]; _Pragma("unroll") for(int r=2;r<16;++r)sacc+=pB0[r]; _Pragma("unroll") for(int r=0;r<16;++r)sacc+=pB1[r]; l_reg+=sacc;
;     pw0=(u32x4){PKW(pB0,0),PKW(pB0,2),PKW(pB0,4),PKW(pB0,6)};pw1=(u32x4){PKW(pB0,8),PKW(pB0,10),PKW(pB0,12),PKW(pB0,14)};pw2=(u32x4){PKW(pB1,0),PKW(pB1,2),PKW(pB1,4),PKW(pB1,6)};pw3=(u32x4){PKW(pB1,8),PKW(pB1,10),PKW(pB1,12),PKW(pB1,14)};
;     SBAR(); pv(o,vb0+sv_cur,PAF(0),PAF(1),PAF(2),PAF(3)); if(VH==2){ SBAR(); pv(o+2*(VH-1),vb0+sv_cur+8192,PAF(0),PAF(1),PAF(2),PAF(3)); } }
;     ...
;   {auto rr=__builtin_amdgcn_permlane32_swap(__float_as_uint(l_reg),__float_as_uint(l_reg),false,false);l_reg=__uint_as_float(rr[0])+__uint_as_float(rr[1]);}
;   if(hi==0)wsf[32+r32]=l_reg;
;   asm volatile("s_waitcnt lgkmcnt(0)\n\ts_barrier":::"memory");
.LBB0_1139:
	v_add_f32_e32 v66, v98, v99
	v_add_f32_e32 v66, v100, v66
	v_add_f32_e32 v66, v101, v66
	v_add_f32_e32 v66, v102, v66
	v_add_f32_e32 v66, v103, v66
	v_add_f32_e32 v66, v104, v66
	v_add_f32_e32 v66, v105, v66
	v_add_f32_e32 v66, v106, v66
	v_add_f32_e32 v66, v107, v66
	v_add_f32_e32 v66, v108, v66
	v_add_f32_e32 v66, v109, v66
	v_add_f32_e32 v66, v110, v66
	v_add_f32_e32 v66, v111, v66
	v_add_f32_e32 v66, v112, v66
	v_add_f32_e32 v66, v113, v66
	v_add_f32_e32 v66, v66, v114
	v_add_f32_e32 v66, v115, v66
	v_add_f32_e32 v66, v116, v66
	v_add_f32_e32 v66, v117, v66
	v_add_f32_e32 v66, v118, v66
	v_add_f32_e32 v66, v119, v66
	v_add_f32_e32 v66, v120, v66
	v_add_f32_e32 v66, v121, v66
	v_add_f32_e32 v66, v122, v66
	v_add_f32_e32 v66, v123, v66
	s_and_b32 s6, s56, 0x3fffffc0
	v_add_f32_e32 v66, v124, v66
	s_lshl_b32 s6, s6, 2
	v_add_f32_e32 v66, v125, v66
	s_add_i32 s8, s6, 0
	v_add_f32_e32 v66, v126, v66
	s_add_i32 s8, s8, 0x14000
	v_add_f32_e32 v66, v127, v66
	s_cmp_lg_u32 0, -1
	v_add_f32_e32 v66, v128, v66
	s_cselect_b32 s6, 0, 0
	v_add_f32_e32 v66, v129, v66
	s_add_i32 s6, s6, 0x8000
	v_add_f32_e32 v0, v66, v0
	v_cvt_pk_bf16_f32 v66, v98, v99
	v_add3_u32 v82, v197, s6, v195
	v_cvt_pk_bf16_f32 v67, v100, v101
	v_cvt_pk_bf16_f32 v68, v102, v103
	v_cvt_pk_bf16_f32 v69, v104, v105
	v_cvt_pk_bf16_f32 v70, v106, v107
	v_cvt_pk_bf16_f32 v71, v108, v109
	v_cvt_pk_bf16_f32 v72, v110, v111
	v_cvt_pk_bf16_f32 v73, v112, v113
	v_cvt_pk_bf16_f32 v74, v114, v115
	v_cvt_pk_bf16_f32 v75, v116, v117
	v_cvt_pk_bf16_f32 v76, v118, v119
	v_cvt_pk_bf16_f32 v77, v120, v121
	v_cvt_pk_bf16_f32 v78, v122, v123
	v_cvt_pk_bf16_f32 v79, v124, v125
	v_cvt_pk_bf16_f32 v80, v126, v127
	v_cvt_pk_bf16_f32 v81, v128, v129
	v_add3_u32 v102, v82, v196, s83
	s_waitcnt vmcnt(0)
	s_barrier
	ds_read_b64_tr_b16 v[82:83],v102 offset:0
	ds_read_b64_tr_b16 v[84:85],v102 offset:512
	ds_read_b64_tr_b16 v[86:87],v102 offset:1024
	ds_read_b64_tr_b16 v[88:89],v102 offset:1536
	ds_read_b64_tr_b16 v[90:91],v102 offset:2048
	ds_read_b64_tr_b16 v[92:93],v102 offset:2560
	ds_read_b64_tr_b16 v[94:95],v102 offset:3072
	ds_read_b64_tr_b16 v[96:97],v102 offset:3584
	s_waitcnt lgkmcnt(0)
	s_nop 0
	v_mfma_f32_32x32x16_bf16 v[50:65], v[66:69], v[82:85], v[50:65]
	ds_read_b64_tr_b16 v[82:83],v102 offset:4096
	ds_read_b64_tr_b16 v[84:85],v102 offset:4608
	v_mfma_f32_32x32x16_bf16 v[50:65], v[70:73], v[86:89], v[50:65]
	ds_read_b64_tr_b16 v[86:87],v102 offset:5120
	ds_read_b64_tr_b16 v[88:89],v102 offset:5632
	v_mfma_f32_32x32x16_bf16 v[50:65], v[74:77], v[90:93], v[50:65]
	ds_read_b64_tr_b16 v[90:91],v102 offset:6144
	ds_read_b64_tr_b16 v[92:93],v102 offset:6656
	ds_read_b64_tr_b16 v[98:99],v102 offset:7168
	ds_read_b64_tr_b16 v[100:101],v102 offset:7680
	s_waitcnt lgkmcnt(0)
	v_mfma_f32_32x32x16_bf16 v[50:65], v[78:81], v[94:97], v[50:65]
	v_mfma_f32_32x32x16_bf16 v[34:49], v[66:69], v[82:85], v[34:49]
	v_mfma_f32_32x32x16_bf16 v[34:49], v[70:73], v[86:89], v[34:49]
	v_mfma_f32_32x32x16_bf16 v[34:49], v[74:77], v[90:93], v[34:49]
	v_mfma_f32_32x32x16_bf16 v[34:49], v[78:81], v[98:101], v[34:49]
	v_add_u32_e32 v102, 0x2000, v102
	ds_read_b64_tr_b16 v[82:83],v102 offset:0
	ds_read_b64_tr_b16 v[84:85],v102 offset:512
	ds_read_b64_tr_b16 v[86:87],v102 offset:1024
	ds_read_b64_tr_b16 v[88:89],v102 offset:1536
	ds_read_b64_tr_b16 v[90:91],v102 offset:2048
	ds_read_b64_tr_b16 v[92:93],v102 offset:2560
	ds_read_b64_tr_b16 v[94:95],v102 offset:3072
	ds_read_b64_tr_b16 v[96:97],v102 offset:3584
	s_waitcnt lgkmcnt(0)
	s_nop 0
	v_mfma_f32_32x32x16_bf16 v[18:33], v[66:69], v[82:85], v[18:33]
	ds_read_b64_tr_b16 v[82:83],v102 offset:4096
	ds_read_b64_tr_b16 v[84:85],v102 offset:4608
	v_mfma_f32_32x32x16_bf16 v[18:33], v[70:73], v[86:89], v[18:33]
	ds_read_b64_tr_b16 v[86:87],v102 offset:5120
	ds_read_b64_tr_b16 v[88:89],v102 offset:5632
	v_mfma_f32_32x32x16_bf16 v[18:33], v[74:77], v[90:93], v[18:33]
	ds_read_b64_tr_b16 v[90:91],v102 offset:6144
	ds_read_b64_tr_b16 v[92:93],v102 offset:6656
	ds_read_b64_tr_b16 v[98:99],v102 offset:7168
	ds_read_b64_tr_b16 v[100:101],v102 offset:7680
	s_waitcnt lgkmcnt(0)
	v_mfma_f32_32x32x16_bf16 v[18:33], v[78:81], v[94:97], v[18:33]
	v_mfma_f32_32x32x16_bf16 v[2:17], v[66:69], v[82:85], v[2:17]
	v_mov_b32_e32 v66, v0
	s_nop 1
	v_permlane32_swap_b32_e32 v0, v66
	v_cmp_gt_u32_e32 vcc, 32, v193
	v_mfma_f32_32x32x16_bf16 v[2:17], v[70:73], v[86:89], v[2:17]
	v_mfma_f32_32x32x16_bf16 v[2:17], v[74:77], v[90:93], v[2:17]
	v_mfma_f32_32x32x16_bf16 v[2:17], v[78:81], v[98:101], v[2:17]
	s_and_saveexec_b64 s[6:7], vcc
	v_lshl_add_u32 v67, v185, 2, s8
	v_add_f32_e32 v0, v0, v66
	ds_write_b32 v67, v0 offset:128
	s_or_b64 exec, exec, s[6:7]
	s_waitcnt lgkmcnt(0)
	s_barrier
; __device__ __forceinline__ int crow(int r,int hi){return (r&3)+8*(r>>2)+4*hi;}
; __device__ __forceinline__ unsigned cvtpk_s(float lo,float hi){f32x2_t v={lo,hi};bf16x2_t b=__builtin_convertvector(v,bf16x2_t);return __builtin_bit_cast(unsigned,b);}
; template<int VH,bool HAS_BIAS,int MODE> __device__ __forceinline__ void attn_unit2(const bf16*Qb,int qp,const bf16*__restrict__ Kb,int kp,const bf16*__restrict__ Vb,int vp,bf16*Ob,int op,int q0,int NT,const float*relb,char*shm,float lam,const float*subg,float gmul){
;     ...
;   if(HAS_BIAS){ const float L2E=1.4426950408889634f; cb=L2E*relb[15*8]; ca=L2E*relb[31*8];
;     for(int i=tid;i<768;i+=512){ const int rel=i-384; const int n=rel<0?-rel:rel; int bk=n<8?n:(8+(31-__builtin_clz((unsigned)(n*n)))-6); if(n>=8&&bk>15)bk=15; if(rel>0)bk+=16; btab[i]=L2E*relb[bk*8]; } }
;     ...
;   float rli[16];
;   #pragma unroll
;   for(int r=0;r<16;++r)rli[r]=__builtin_amdgcn_rcpf(wsf[32+crow(r,hi)]);
;   bf16*Ow=Ob+(long)(q0+wid*QBLK)*op;
;   typedef __attribute__((address_space(3))) unsigned lds_u32;
;   lds_u32* park=(lds_u32*)((lds_ptr_)shm+LM::BYTES)+tid;
;   if(MODE==1){
;     #pragma unroll
;     for(int d0=0;d0<2*VH;++d0)
;       #pragma unroll
;       for(int r=0;r<16;r+=2)park[(d0*8+(r>>1))*512]=cvtpk_s(o[d0][r]*rli[r],o[d0][r+1]*rli[r+1]);
	v_lshl_add_u32 v0, v194, 2, s8
	ds_read_b128 v[66:69], v0 offset:128
	ds_read_b128 v[70:73], v0 offset:160
	s_waitcnt lgkmcnt(1)
	v_rcp_f32_e32 v74, v66
	v_rcp_f32_e32 v75, v67
	v_rcp_f32_e32 v76, v68
	v_rcp_f32_e32 v77, v69
	ds_read_b128 v[66:69], v0 offset:192
	s_waitcnt lgkmcnt(1)
	v_rcp_f32_e32 v78, v70
	v_rcp_f32_e32 v79, v71
	v_rcp_f32_e32 v80, v72
	v_rcp_f32_e32 v81, v73
	ds_read_b128 v[70:73], v0 offset:224
	v_pk_mul_f32 v[50:51], v[50:51], v[74:75]
	v_lshl_add_u32 v0, v184, 2, 0
	v_cvt_pk_bf16_f32 v82, v50, v51
	v_pk_mul_f32 v[50:51], v[52:53], v[76:77]
	s_waitcnt lgkmcnt(1)
	v_rcp_f32_e32 v66, v66
	v_rcp_f32_e32 v67, v67
	v_add_u32_e32 v0, 0x15400, v0
	v_cvt_pk_bf16_f32 v50, v50, v51
	v_rcp_f32_e32 v68, v68
	v_rcp_f32_e32 v69, v69
	ds_write2st64_b32 v0, v82, v50 offset1:8
	v_pk_mul_f32 v[50:51], v[54:55], v[78:79]
	s_waitcnt lgkmcnt(1)
	v_rcp_f32_e32 v70, v70
	v_cvt_pk_bf16_f32 v52, v50, v51
	v_pk_mul_f32 v[50:51], v[56:57], v[80:81]
	v_rcp_f32_e32 v71, v71
	v_cvt_pk_bf16_f32 v50, v50, v51
	v_rcp_f32_e32 v72, v72
	v_rcp_f32_e32 v73, v73
	ds_write2st64_b32 v0, v52, v50 offset0:16 offset1:24
	v_pk_mul_f32 v[50:51], v[58:59], v[66:67]
	v_pk_mul_f32 v[34:35], v[34:35], v[74:75]
	v_cvt_pk_bf16_f32 v52, v50, v51
	v_pk_mul_f32 v[50:51], v[60:61], v[68:69]
	v_pk_mul_f32 v[18:19], v[18:19], v[74:75]
	v_cvt_pk_bf16_f32 v50, v50, v51
	ds_write2st64_b32 v0, v52, v50 offset0:32 offset1:40
	v_pk_mul_f32 v[50:51], v[62:63], v[70:71]
	v_pk_mul_f32 v[2:3], v[2:3], v[74:75]
	v_cvt_pk_bf16_f32 v52, v50, v51
	v_pk_mul_f32 v[50:51], v[64:65], v[72:73]
	v_mov_b32_e32 v184, v182
	v_cvt_pk_bf16_f32 v50, v50, v51
	ds_write2st64_b32 v0, v52, v50 offset0:48 offset1:56
	v_cvt_pk_bf16_f32 v50, v34, v35
	v_pk_mul_f32 v[34:35], v[36:37], v[76:77]
	s_nop 0
	v_cvt_pk_bf16_f32 v34, v34, v35
	ds_write2st64_b32 v0, v50, v34 offset0:64 offset1:72
	v_pk_mul_f32 v[34:35], v[38:39], v[78:79]
	s_nop 0
	v_cvt_pk_bf16_f32 v36, v34, v35
	v_pk_mul_f32 v[34:35], v[40:41], v[80:81]
	s_nop 0
	v_cvt_pk_bf16_f32 v34, v34, v35
	ds_write2st64_b32 v0, v36, v34 offset0:80 offset1:88
	v_pk_mul_f32 v[34:35], v[42:43], v[66:67]
	s_nop 0
	v_cvt_pk_bf16_f32 v36, v34, v35
	v_pk_mul_f32 v[34:35], v[44:45], v[68:69]
	s_nop 0
	v_cvt_pk_bf16_f32 v34, v34, v35
	ds_write2st64_b32 v0, v36, v34 offset0:96 offset1:104
	v_pk_mul_f32 v[34:35], v[46:47], v[70:71]
	s_nop 0
	v_cvt_pk_bf16_f32 v36, v34, v35
	v_pk_mul_f32 v[34:35], v[48:49], v[72:73]
	s_nop 0
	v_cvt_pk_bf16_f32 v34, v34, v35
	ds_write2st64_b32 v0, v36, v34 offset0:112 offset1:120
	v_cvt_pk_bf16_f32 v34, v18, v19
	v_pk_mul_f32 v[18:19], v[20:21], v[76:77]
	s_nop 0
	v_cvt_pk_bf16_f32 v18, v18, v19
	ds_write2st64_b32 v0, v34, v18 offset0:128 offset1:136
	v_pk_mul_f32 v[18:19], v[22:23], v[78:79]
	s_nop 0
	v_cvt_pk_bf16_f32 v20, v18, v19
	v_pk_mul_f32 v[18:19], v[24:25], v[80:81]
	s_nop 0
	v_cvt_pk_bf16_f32 v18, v18, v19
	ds_write2st64_b32 v0, v20, v18 offset0:144 offset1:152
	v_pk_mul_f32 v[18:19], v[26:27], v[66:67]
	s_nop 0
	v_cvt_pk_bf16_f32 v20, v18, v19
	v_pk_mul_f32 v[18:19], v[28:29], v[68:69]
	s_nop 0
	v_cvt_pk_bf16_f32 v18, v18, v19
	ds_write2st64_b32 v0, v20, v18 offset0:160 offset1:168
	v_pk_mul_f32 v[18:19], v[30:31], v[70:71]
	s_nop 0
	v_cvt_pk_bf16_f32 v20, v18, v19
	v_pk_mul_f32 v[18:19], v[32:33], v[72:73]
	s_nop 0
	v_cvt_pk_bf16_f32 v18, v18, v19
	ds_write2st64_b32 v0, v20, v18 offset0:176 offset1:184
	v_cvt_pk_bf16_f32 v18, v2, v3
	v_pk_mul_f32 v[2:3], v[4:5], v[76:77]
	s_nop 0
	v_cvt_pk_bf16_f32 v2, v2, v3
	ds_write2st64_b32 v0, v18, v2 offset0:192 offset1:200
	v_pk_mul_f32 v[2:3], v[6:7], v[78:79]
	s_nop 0
	v_cvt_pk_bf16_f32 v4, v2, v3
	v_pk_mul_f32 v[2:3], v[8:9], v[80:81]
	s_nop 0
	v_cvt_pk_bf16_f32 v2, v2, v3
	ds_write2st64_b32 v0, v4, v2 offset0:208 offset1:216
	v_pk_mul_f32 v[2:3], v[10:11], v[66:67]
	s_nop 0
	v_cvt_pk_bf16_f32 v4, v2, v3
	v_pk_mul_f32 v[2:3], v[12:13], v[68:69]
	s_nop 0
	v_cvt_pk_bf16_f32 v2, v2, v3
	ds_write2st64_b32 v0, v4, v2 offset0:224 offset1:232
	v_pk_mul_f32 v[2:3], v[14:15], v[70:71]
	s_nop 0
	v_cvt_pk_bf16_f32 v4, v2, v3
	v_pk_mul_f32 v[2:3], v[16:17], v[72:73]
	s_nop 0
	v_cvt_pk_bf16_f32 v2, v2, v3
	ds_write2st64_b32 v0, v4, v2 offset0:240 offset1:248
	s_waitcnt lgkmcnt(0)
	s_barrier
	s_load_dwordx2 s[42:43], s[0:1], 0xb8
	global_load_dword v0, v1, s[40:41] offset:480
	global_load_dword v34, v1, s[40:41] offset:992
	v_readfirstlane_b32 s81, v184
	v_cmp_gt_i32_e32 vcc, s64, v184
	s_and_saveexec_b64 s[54:55], vcc
	s_branch .LBB0_1153
	v_max_i32_e32 v2, 0x100, v184
	v_sub_u32_e32 v2, v2, v184
	v_add_u32_e32 v3, 0x1ff, v2
	v_cmp_lt_u32_e32 vcc, s63, v3
	s_mov_b64 s[6:7], -1
	v_mov_b32_e32 v2, v184
	s_and_saveexec_b64 s[56:57], vcc
	s_cbranch_execz .LBB0_1150
	v_lshrrev_b32_e32 v4, 9, v3
	v_add_u32_e32 v185, 0x200, v184
	v_add_u32_e32 v5, -1, v4
	v_cmp_lt_u32_e32 vcc, 1, v5
	v_mov_b32_e32 v6, 0
	v_mov_b64_e32 v[2:3], v[184:185]
	s_and_saveexec_b64 s[58:59], vcc
	s_cbranch_execz .LBB0_1147
	v_lshrrev_b32_e32 v2, 1, v5
	v_add_u32_e32 v2, 1, v2
	v_and_b32_e32 v6, -2, v2
	v_lshl_add_u32 v7, v184, 2, s65
	s_mov_b32 s33, 0
	s_mov_b64 s[60:61], 0
	v_mov_b64_e32 v[2:3], v[184:185]

.LBB0_1190:
	s_waitcnt lgkmcnt(14)
	v_mfma_f32_32x32x16_bf16 v[18:33], v[142:145], v[110:113], v[18:33]
	v_exp_f32_e32 v66, v66
	v_exp_f32_e32 v67, v67
	s_waitcnt lgkmcnt(12)
	v_mfma_f32_32x32x16_bf16 v[2:17], v[142:145], v[174:177], v[2:17]
	v_exp_f32_e32 v68, v68
	v_exp_f32_e32 v69, v69
	s_waitcnt lgkmcnt(10)
	v_mfma_f32_32x32x16_bf16 v[18:33], v[138:141], v[118:121], v[18:33]
	v_exp_f32_e32 v70, v70
	v_exp_f32_e32 v71, v71
	s_waitcnt lgkmcnt(8)
	v_mfma_f32_32x32x16_bf16 v[2:17], v[138:141], v[122:125], v[2:17]
	v_exp_f32_e32 v72, v72
	v_exp_f32_e32 v73, v73
	s_waitcnt lgkmcnt(6)
	v_mfma_f32_32x32x16_bf16 v[18:33], v[134:137], v[126:129], v[18:33]
	v_exp_f32_e32 v74, v74
	v_exp_f32_e32 v75, v75
	s_waitcnt lgkmcnt(4)
	v_mfma_f32_32x32x16_bf16 v[2:17], v[134:137], v[98:101], v[2:17]
	v_exp_f32_e32 v76, v76
	v_exp_f32_e32 v77, v77
	s_waitcnt lgkmcnt(2)
	v_mfma_f32_32x32x16_bf16 v[18:33], v[130:133], v[102:105], v[18:33]
	v_exp_f32_e32 v78, v78
	v_exp_f32_e32 v79, v79
	s_waitcnt lgkmcnt(0)
	v_mfma_f32_32x32x16_bf16 v[2:17], v[130:133], v[106:109], v[2:17]
	v_exp_f32_e32 v80, v80
	v_exp_f32_e32 v81, v81
	s_mov_b64 s[46:47], -1
	s_and_b64 vcc, exec, s[44:45]
	s_cbranch_vccz .LBB0_1196
	s_mov_b64 s[44:45], -1
	s_and_b64 vcc, exec, s[40:41]
	s_cbranch_vccz .LBB0_1193
	s_waitcnt vmcnt(2) lgkmcnt(0)
	s_barrier
	s_mov_b64 s[44:45], 0

; #define SBAR() __builtin_amdgcn_sched_barrier(0)
;   #define PKW(P,B) cvtpk_s(P[B],P[B+1])
; __device__ __forceinline__ void pv(f32x16*o,int vb,bf16x8 pa0,bf16x8 pa1,bf16x8 pa2,bf16x8 pa3){
;   #pragma unroll
;   for(int d0=0;d0<2;++d0){s16x4 lo[4],hi[4];
;     #pragma unroll
;     for(int ks=0;ks<4;++ks){
;       asm volatile("ds_read_b64_tr_b16 %0,%1 offset:%c2":"=&v"(lo[ks]):"v"(vb),"i"(d0*4096+ks*1024):"memory");
;       asm volatile("ds_read_b64_tr_b16 %0,%1 offset:%c2":"=&v"(hi[ks]):"v"(vb),"i"(d0*4096+ks*1024+512):"memory");}
;     asm volatile("s_waitcnt lgkmcnt(0)":::"memory");SBAR();
;     ...
;     o[d0]=__builtin_amdgcn_mfma_f32_32x32x16_bf16(pa0,PK(0),o[d0],0,0,0);
;     o[d0]=__builtin_amdgcn_mfma_f32_32x32x16_bf16(pa1,PK(1),o[d0],0,0,0);
;     o[d0]=__builtin_amdgcn_mfma_f32_32x32x16_bf16(pa2,PK(2),o[d0],0,0,0);
;     o[d0]=__builtin_amdgcn_mfma_f32_32x32x16_bf16(pa3,PK(3),o[d0],0,0,0);
;     ...
;   }
; }
; template<int VH,bool HAS_BIAS,int MODE> __device__ __forceinline__ void attn_unit2(const bf16*Qb,int qp,const bf16*__restrict__ Kb,int kp,const bf16*__restrict__ Vb,int vp,bf16*Ob,int op,int q0,int NT,const float*relb,char*shm,float lam,const float*subg,float gmul){
;     ...
;   { float sacc=pB0[0]+pB0[1]; _Pragma("unroll") for(int r=2;r<16;++r)sacc+=pB0[r]; _Pragma("unroll") for(int r=0;r<16;++r)sacc+=pB1[r]; l_reg+=sacc;
;     pw0=(u32x4){PKW(pB0,0),PKW(pB0,2),PKW(pB0,4),PKW(pB0,6)};pw1=(u32x4){PKW(pB0,8),PKW(pB0,10),PKW(pB0,12),PKW(pB0,14)};pw2=(u32x4){PKW(pB1,0),PKW(pB1,2),PKW(pB1,4),PKW(pB1,6)};pw3=(u32x4){PKW(pB1,8),PKW(pB1,10),PKW(pB1,12),PKW(pB1,14)};
;     SBAR(); pv(o,vb0+sv_cur,PAF(0),PAF(1),PAF(2),PAF(3)); if(VH==2){ SBAR(); pv(o+2*(VH-1),vb0+sv_cur+8192,PAF(0),PAF(1),PAF(2),PAF(3)); } }
;     ...
;   {auto rr=__builtin_amdgcn_permlane32_swap(__float_as_uint(l_reg),__float_as_uint(l_reg),false,false);l_reg=__uint_as_float(rr[0])+__uint_as_float(rr[1]);}
;   if(hi==0)wsf[32+r32]=l_reg;
.LBB0_1207:
	v_add_f32_e32 v66, v98, v99
	v_add_f32_e32 v66, v100, v66
	v_add_f32_e32 v66, v101, v66
	v_add_f32_e32 v66, v102, v66
	v_add_f32_e32 v66, v103, v66
	v_add_f32_e32 v66, v104, v66
	v_add_f32_e32 v66, v105, v66
	v_add_f32_e32 v66, v106, v66
	v_add_f32_e32 v66, v107, v66
	v_add_f32_e32 v66, v108, v66
	v_add_f32_e32 v66, v109, v66
	v_add_f32_e32 v66, v110, v66
	v_add_f32_e32 v66, v111, v66
	v_add_f32_e32 v66, v112, v66
	v_add_f32_e32 v66, v113, v66
	v_add_f32_e32 v66, v66, v114
	v_add_f32_e32 v66, v115, v66
	v_add_f32_e32 v66, v116, v66
	v_add_f32_e32 v66, v117, v66
	v_add_f32_e32 v66, v118, v66
	v_add_f32_e32 v66, v119, v66
	v_add_f32_e32 v66, v120, v66
	v_add_f32_e32 v66, v121, v66
	v_add_f32_e32 v66, v122, v66
	v_add_f32_e32 v66, v123, v66
	v_add_f32_e32 v66, v124, v66
	v_add_f32_e32 v66, v125, v66
	v_add_f32_e32 v66, v126, v66
	s_and_b32 s6, s81, 0x3fffffc0
	v_add_f32_e32 v66, v127, v66
	s_lshl_b32 s6, s6, 2
	v_add_f32_e32 v66, v128, v66
	s_add_i32 s8, s6, 0
	v_add_f32_e32 v66, v129, v66
	s_add_i32 s8, s8, 0x14000
	v_add_f32_e32 v0, v66, v0
	v_cvt_pk_bf16_f32 v66, v98, v99
	v_cvt_pk_bf16_f32 v67, v100, v101
	v_cvt_pk_bf16_f32 v68, v102, v103
	v_cvt_pk_bf16_f32 v69, v104, v105
	v_cvt_pk_bf16_f32 v70, v106, v107
	v_cvt_pk_bf16_f32 v71, v108, v109
	v_cvt_pk_bf16_f32 v72, v110, v111
	v_cvt_pk_bf16_f32 v73, v112, v113
	v_cvt_pk_bf16_f32 v74, v114, v115
	v_cvt_pk_bf16_f32 v75, v116, v117
	v_cvt_pk_bf16_f32 v76, v118, v119
	v_cvt_pk_bf16_f32 v77, v120, v121
	v_cvt_pk_bf16_f32 v78, v122, v123
	v_cvt_pk_bf16_f32 v79, v124, v125
	v_cvt_pk_bf16_f32 v80, v126, v127
	v_cvt_pk_bf16_f32 v81, v128, v129
	s_cmp_lg_u32 0, -1
	s_cselect_b32 s6, 0, 0
	s_add_i32 s6, s6, 0x8000
	v_add3_u32 v82, v199, s6, v200
	v_add3_u32 v102, v82, v201, s53
	s_waitcnt vmcnt(0)
	s_barrier
	ds_read_b64_tr_b16 v[82:83],v102 offset:0
	ds_read_b64_tr_b16 v[84:85],v102 offset:512
	ds_read_b64_tr_b16 v[86:87],v102 offset:1024
	ds_read_b64_tr_b16 v[88:89],v102 offset:1536
	ds_read_b64_tr_b16 v[90:91],v102 offset:2048
	ds_read_b64_tr_b16 v[92:93],v102 offset:2560
	ds_read_b64_tr_b16 v[94:95],v102 offset:3072
	ds_read_b64_tr_b16 v[96:97],v102 offset:3584
	s_waitcnt lgkmcnt(0)
	s_nop 0
	v_mfma_f32_32x32x16_bf16 v[50:65], v[66:69], v[82:85], v[50:65]
	ds_read_b64_tr_b16 v[82:83],v102 offset:4096
	ds_read_b64_tr_b16 v[84:85],v102 offset:4608
	v_mfma_f32_32x32x16_bf16 v[50:65], v[70:73], v[86:89], v[50:65]
	ds_read_b64_tr_b16 v[86:87],v102 offset:5120
	ds_read_b64_tr_b16 v[88:89],v102 offset:5632
	v_mfma_f32_32x32x16_bf16 v[50:65], v[74:77], v[90:93], v[50:65]
	ds_read_b64_tr_b16 v[90:91],v102 offset:6144
	ds_read_b64_tr_b16 v[92:93],v102 offset:6656
	ds_read_b64_tr_b16 v[98:99],v102 offset:7168
	ds_read_b64_tr_b16 v[100:101],v102 offset:7680
	s_waitcnt lgkmcnt(0)
	v_mfma_f32_32x32x16_bf16 v[50:65], v[78:81], v[94:97], v[50:65]
	v_mfma_f32_32x32x16_bf16 v[34:49], v[66:69], v[82:85], v[34:49]
	v_mfma_f32_32x32x16_bf16 v[34:49], v[70:73], v[86:89], v[34:49]
	v_mfma_f32_32x32x16_bf16 v[34:49], v[74:77], v[90:93], v[34:49]
	v_mfma_f32_32x32x16_bf16 v[34:49], v[78:81], v[98:101], v[34:49]
	v_add_u32_e32 v102, 0x2000, v102
	ds_read_b64_tr_b16 v[82:83],v102 offset:0
	ds_read_b64_tr_b16 v[84:85],v102 offset:512
	ds_read_b64_tr_b16 v[86:87],v102 offset:1024
	ds_read_b64_tr_b16 v[88:89],v102 offset:1536
	ds_read_b64_tr_b16 v[90:91],v102 offset:2048
	ds_read_b64_tr_b16 v[92:93],v102 offset:2560
	ds_read_b64_tr_b16 v[94:95],v102 offset:3072
	ds_read_b64_tr_b16 v[96:97],v102 offset:3584
	s_waitcnt lgkmcnt(0)
	s_nop 0
	v_mfma_f32_32x32x16_bf16 v[18:33], v[66:69], v[82:85], v[18:33]
	ds_read_b64_tr_b16 v[82:83],v102 offset:4096
	ds_read_b64_tr_b16 v[84:85],v102 offset:4608
	v_mfma_f32_32x32x16_bf16 v[18:33], v[70:73], v[86:89], v[18:33]
	ds_read_b64_tr_b16 v[86:87],v102 offset:5120
	ds_read_b64_tr_b16 v[88:89],v102 offset:5632
	v_mfma_f32_32x32x16_bf16 v[18:33], v[74:77], v[90:93], v[18:33]
	ds_read_b64_tr_b16 v[90:91],v102 offset:6144
	ds_read_b64_tr_b16 v[92:93],v102 offset:6656
	ds_read_b64_tr_b16 v[98:99],v102 offset:7168
	ds_read_b64_tr_b16 v[100:101],v102 offset:7680
	s_waitcnt lgkmcnt(0)
	v_mfma_f32_32x32x16_bf16 v[18:33], v[78:81], v[94:97], v[18:33]
	v_mfma_f32_32x32x16_bf16 v[2:17], v[66:69], v[82:85], v[2:17]
	v_mov_b32_e32 v66, v0
	s_nop 1
	v_permlane32_swap_b32_e32 v0, v66
	v_cmp_gt_u32_e32 vcc, 32, v197
	v_mfma_f32_32x32x16_bf16 v[2:17], v[70:73], v[86:89], v[2:17]
	v_mfma_f32_32x32x16_bf16 v[2:17], v[74:77], v[90:93], v[2:17]
	v_mfma_f32_32x32x16_bf16 v[2:17], v[78:81], v[98:101], v[2:17]
	s_and_saveexec_b64 s[6:7], vcc
	s_cbranch_execz .LBB0_1068
	v_lshl_add_u32 v67, v185, 2, s8
	v_add_f32_e32 v0, v0, v66
	ds_write_b32 v67, v0 offset:128
	s_branch .LBB0_1068
